# EpiBranch3 third segment: gate tile fetched by the last K-trip's re-stage LDS-DMA loads, read back with ds_read in that segment's epilogue
# speedup vs baseline: 1.0064x; 1.0064x over previous
.LBB0_1673:
	s_add_i32 s78, s74, 2
	s_add_u32 s22, s8, 0x80
	s_addc_u32 s23, s9, 0
	s_add_i32 s67, 0, 0x10000
	s_cmp_eq_u32 s94, s74
	s_cselect_b32 s75, s71, s23
	s_cselect_b32 s74, s70, s22
	v_add_u32_e32 v96, s67, v238
	s_cselect_b32 s23, s73, vcc_lo
	s_cselect_b32 s22, s72, s69
	s_cselect_b32 s98, 1, 0
	s_add_i32 s79, 0, 0x14000
	ds_read_b128 v[132:135], v96
	ds_read_b128 v[136:139], v96 offset:1024
	ds_read_b128 v[140:143], v96 offset:2048
	ds_read_b128 v[144:147], v96 offset:3072
	v_add_u32_e32 v96, s79, v238
	ds_read_b128 v[148:151], v96
	ds_read_b128 v[152:155], v96 offset:1024
	ds_read_b128 v[156:159], v96 offset:2048
	ds_read_b128 v[160:163], v96 offset:3072
	v_lshl_add_u64 v[98:99], s[8:9], 0, v[198:199]
	s_add_i32 m0, s83, 0xc000
	ds_read_b128 v[164:167], v239
	ds_read_b128 v[168:171], v239 offset:1024
	ds_read_b128 v[172:175], v239 offset:2048
	ds_read_b128 v[176:179], v239 offset:3072
	ds_read_b128 v[180:183], v239 offset:4096
	ds_read_b128 v[184:187], v239 offset:5120
	ds_read_b128 v[200:203], v239 offset:6144
	ds_read_b128 v[204:207], v239 offset:7168
	global_load_lds_dwordx4 v[98:99], off
	v_lshl_add_u64 v[98:99], s[8:9], 0, v[196:197]
	s_add_i32 m0, s83, 0xe000
	s_nop 0
	global_load_lds_dwordx4 v[98:99], off
	s_waitcnt vmcnt(8)
	s_waitcnt lgkmcnt(0)
	s_barrier
	s_setprio 1
	s_waitcnt lgkmcnt(0)
	v_mfma_f32_16x16x32_bf16 v[128:131], v[132:135], v[164:167], v[128:131]
	v_mfma_f32_16x16x32_bf16 v[124:127], v[140:143], v[164:167], v[124:127]
	v_mfma_f32_16x16x32_bf16 v[120:123], v[132:135], v[172:175], v[120:123]
	v_mfma_f32_16x16x32_bf16 v[116:119], v[140:143], v[172:175], v[116:119]
	v_mfma_f32_16x16x32_bf16 v[112:115], v[132:135], v[180:183], v[112:115]
	v_mfma_f32_16x16x32_bf16 v[108:111], v[140:143], v[180:183], v[108:111]
	v_mfma_f32_16x16x32_bf16 v[104:107], v[132:135], v[200:203], v[104:107]
	v_mfma_f32_16x16x32_bf16 v[98:101], v[140:143], v[200:203], v[100:103]
	v_mfma_f32_16x16x32_bf16 v[128:131], v[136:139], v[168:171], v[128:131]
	v_mfma_f32_16x16x32_bf16 v[124:127], v[144:147], v[168:171], v[124:127]
	v_mfma_f32_16x16x32_bf16 v[120:123], v[136:139], v[176:179], v[120:123]
	v_mfma_f32_16x16x32_bf16 v[116:119], v[144:147], v[176:179], v[116:119]
	v_mfma_f32_16x16x32_bf16 v[112:115], v[136:139], v[184:187], v[112:115]
	v_mfma_f32_16x16x32_bf16 v[108:111], v[144:147], v[184:187], v[108:111]
	v_mfma_f32_16x16x32_bf16 v[104:107], v[136:139], v[204:207], v[104:107]
	v_mfma_f32_16x16x32_bf16 v[98:101], v[144:147], v[204:207], v[98:101]
	s_setprio 0
	s_setprio 1
	v_mfma_f32_16x16x32_bf16 v[92:95], v[148:151], v[164:167], v[92:95]
	v_mfma_f32_16x16x32_bf16 v[88:91], v[156:159], v[164:167], v[88:91]
	v_mfma_f32_16x16x32_bf16 v[84:87], v[148:151], v[172:175], v[84:87]
	v_mfma_f32_16x16x32_bf16 v[80:83], v[156:159], v[172:175], v[80:83]
	v_mfma_f32_16x16x32_bf16 v[76:79], v[148:151], v[180:183], v[76:79]
	v_mfma_f32_16x16x32_bf16 v[72:75], v[156:159], v[180:183], v[72:75]
	v_mfma_f32_16x16x32_bf16 v[68:71], v[148:151], v[200:203], v[68:71]
	v_mfma_f32_16x16x32_bf16 v[64:67], v[156:159], v[200:203], v[64:67]
	v_mfma_f32_16x16x32_bf16 v[92:95], v[152:155], v[168:171], v[92:95]
	v_mfma_f32_16x16x32_bf16 v[88:91], v[160:163], v[168:171], v[88:91]
	v_mfma_f32_16x16x32_bf16 v[84:87], v[152:155], v[176:179], v[84:87]
	v_mfma_f32_16x16x32_bf16 v[80:83], v[160:163], v[176:179], v[80:83]
	v_mfma_f32_16x16x32_bf16 v[76:79], v[152:155], v[184:187], v[76:79]
	v_mfma_f32_16x16x32_bf16 v[72:75], v[160:163], v[184:187], v[72:75]
	v_mfma_f32_16x16x32_bf16 v[68:71], v[152:155], v[204:207], v[68:71]
	v_mfma_f32_16x16x32_bf16 v[64:67], v[160:163], v[204:207], v[64:67]
	s_setprio 0
	s_barrier
	s_cmp_eq_u32 s98, 0
	s_cbranch_scc1 .Lbr3_skip
	s_cmp_lg_u32 s76, 2
	s_cbranch_scc1 .Lbr3_noseg2
	v_lshlrev_b32_e32 v190, 11, v237
	v_lshl_add_u32 v190, v236, 4, v190
	v_add_u32_e32 v194, 0x100, v190
	v_mov_b32_e32 v188, v190
	v_mov_b32_e32 v192, v194
	s_lshl_b32 s22, s77, 8
	s_add_i32 s22, s22, s90
	s_ashr_i32 s23, s22, 31
	s_lshl_b64 s[22:23], s[22:23], 11
	s_lshl_b32 s74, s35, 8
	s_or_b32 s74, s74, s93
	s_lshl_b32 s74, s74, 1
	s_add_u32 s22, s22, s74
	s_addc_u32 s23, s23, 0
	s_add_u32 s22, s22, s87
	s_addc_u32 s23, s23, s88
	s_add_u32 s22, s22, 0x4000000
	s_addc_u32 s23, s23, 0
	s_add_u32 s74, s22, 0x10000
	s_addc_u32 s75, s23, 0
	s_mov_b32 s24, 0x8000
	s_mov_b32 s25, 0
	s_mov_b32 s56, 0x40000
	s_mov_b32 s57, 0
	s_branch .Lbr3_skip
.Lbr3_noseg2:
	s_mov_b32 s98, 0
.Lbr3_skip:
	s_add_i32 s67, s67, s82
	v_lshl_add_u64 v[208:209], s[22:23], 0, v[190:191]
	s_mov_b32 m0, s67
	ds_read_b128 v[164:167], v239 offset:16384
	ds_read_b128 v[168:171], v239 offset:17408
	ds_read_b128 v[172:175], v239 offset:18432
	ds_read_b128 v[176:179], v239 offset:19456
	ds_read_b128 v[180:183], v239 offset:20480
	ds_read_b128 v[184:187], v239 offset:21504
	ds_read_b128 v[200:203], v239 offset:22528
	ds_read_b128 v[204:207], v239 offset:23552
	global_load_lds_dwordx4 v[208:209], off
	s_add_i32 m0, s67, 0x2000
	v_lshl_add_u64 v[210:211], s[22:23], 0, v[194:195]
	s_add_u32 s22, s22, s24
	s_addc_u32 s23, s23, s25
	s_add_i32 s67, s79, s82
	global_load_lds_dwordx4 v[210:211], off
	v_lshl_add_u64 v[212:213], s[22:23], 0, v[190:191]
	s_mov_b32 m0, s67
	v_lshl_add_u64 v[214:215], s[22:23], 0, v[194:195]
	global_load_lds_dwordx4 v[212:213], off
	s_add_i32 m0, s67, 0x2000
	v_lshl_add_u64 v[216:217], s[74:75], 0, v[188:189]
	global_load_lds_dwordx4 v[214:215], off
	s_mov_b32 m0, s83
	v_lshl_add_u64 v[218:219], s[74:75], 0, v[192:193]
	global_load_lds_dwordx4 v[216:217], off
	s_mov_b32 m0, s84
	s_nop 0
	global_load_lds_dwordx4 v[218:219], off
	s_waitcnt vmcnt(8)
	s_waitcnt lgkmcnt(0)
	s_barrier
	s_setprio 1
	s_waitcnt lgkmcnt(0)
	v_mfma_f32_16x16x32_bf16 v[60:63], v[132:135], v[164:167], v[60:63]
	v_mfma_f32_16x16x32_bf16 v[56:59], v[140:143], v[164:167], v[56:59]
	v_mfma_f32_16x16x32_bf16 v[52:55], v[132:135], v[172:175], v[52:55]
	v_mfma_f32_16x16x32_bf16 v[48:51], v[140:143], v[172:175], v[48:51]
	v_mfma_f32_16x16x32_bf16 v[44:47], v[132:135], v[180:183], v[44:47]
	v_mfma_f32_16x16x32_bf16 v[40:43], v[140:143], v[180:183], v[40:43]
	v_mfma_f32_16x16x32_bf16 v[36:39], v[132:135], v[200:203], v[36:39]
	v_mfma_f32_16x16x32_bf16 v[32:35], v[140:143], v[200:203], v[32:35]
	v_mfma_f32_16x16x32_bf16 v[60:63], v[136:139], v[168:171], v[60:63]
	v_mfma_f32_16x16x32_bf16 v[56:59], v[144:147], v[168:171], v[56:59]
	v_mfma_f32_16x16x32_bf16 v[52:55], v[136:139], v[176:179], v[52:55]
	v_mfma_f32_16x16x32_bf16 v[48:51], v[144:147], v[176:179], v[48:51]
	v_mfma_f32_16x16x32_bf16 v[44:47], v[136:139], v[184:187], v[44:47]
	v_mfma_f32_16x16x32_bf16 v[40:43], v[144:147], v[184:187], v[40:43]
	v_mfma_f32_16x16x32_bf16 v[36:39], v[136:139], v[204:207], v[36:39]
	v_mfma_f32_16x16x32_bf16 v[32:35], v[144:147], v[204:207], v[32:35]
	s_setprio 0
	s_setprio 1
	v_mfma_f32_16x16x32_bf16 v[28:31], v[148:151], v[164:167], v[28:31]
	v_mfma_f32_16x16x32_bf16 v[24:27], v[156:159], v[164:167], v[24:27]
	v_mfma_f32_16x16x32_bf16 v[20:23], v[148:151], v[172:175], v[20:23]
	v_mfma_f32_16x16x32_bf16 v[16:19], v[156:159], v[172:175], v[16:19]
	v_mfma_f32_16x16x32_bf16 v[12:15], v[148:151], v[180:183], v[12:15]
	v_mfma_f32_16x16x32_bf16 v[8:11], v[156:159], v[180:183], v[8:11]
	v_mfma_f32_16x16x32_bf16 v[4:7], v[148:151], v[200:203], v[4:7]
	v_mfma_f32_16x16x32_bf16 v[0:3], v[156:159], v[200:203], v[0:3]
	v_mfma_f32_16x16x32_bf16 v[28:31], v[152:155], v[168:171], v[28:31]
	v_mfma_f32_16x16x32_bf16 v[24:27], v[160:163], v[168:171], v[24:27]
	v_mfma_f32_16x16x32_bf16 v[20:23], v[152:155], v[176:179], v[20:23]
	v_mfma_f32_16x16x32_bf16 v[16:19], v[160:163], v[176:179], v[16:19]
	v_mfma_f32_16x16x32_bf16 v[12:15], v[152:155], v[184:187], v[12:15]
	v_mfma_f32_16x16x32_bf16 v[8:11], v[160:163], v[184:187], v[8:11]
	v_mfma_f32_16x16x32_bf16 v[4:7], v[152:155], v[204:207], v[4:7]
	v_mfma_f32_16x16x32_bf16 v[0:3], v[160:163], v[204:207], v[0:3]
	s_setprio 0
	s_barrier
	s_add_i32 s67, 0, 0x18000
	v_add_u32_e32 v96, s67, v238
	s_add_i32 s79, 0, 0x1c000
	ds_read_b128 v[132:135], v96
	ds_read_b128 v[136:139], v96 offset:1024
	ds_read_b128 v[140:143], v96 offset:2048
	ds_read_b128 v[144:147], v96 offset:3072
	v_add_u32_e32 v96, s79, v238
	ds_read_b128 v[148:151], v96
	ds_read_b128 v[152:155], v96 offset:1024
	ds_read_b128 v[156:159], v96 offset:2048
	ds_read_b128 v[160:163], v96 offset:3072
	s_add_u32 s22, s74, s24
	s_addc_u32 s23, s75, s25
	s_mov_b32 m0, s85
	v_lshl_add_u64 v[102:103], s[22:23], 0, v[188:189]
	ds_read_b128 v[164:167], v239 offset:32768
	ds_read_b128 v[168:171], v239 offset:33792
	ds_read_b128 v[172:175], v239 offset:34816
	ds_read_b128 v[176:179], v239 offset:35840
	ds_read_b128 v[180:183], v239 offset:36864
	ds_read_b128 v[184:187], v239 offset:37888
	ds_read_b128 v[200:203], v239 offset:38912
	ds_read_b128 v[204:207], v239 offset:39936
	global_load_lds_dwordx4 v[102:103], off
	v_lshl_add_u64 v[102:103], s[22:23], 0, v[192:193]
	s_mov_b32 m0, s86
	s_nop 0
	global_load_lds_dwordx4 v[102:103], off
	s_cmp_eq_u32 s98, 0
	s_cbranch_scc1 .Lbr3_skipB
	v_lshl_add_u64 v[102:103], v[102:103], 0, s[56:57]
	s_add_i32 m0, s82, 0x23000
	s_nop 0
	global_load_lds_dwordx4 v[102:103], off
	s_mov_b32 s22, 0xffffff00
	s_mov_b32 s23, -1
	v_lshl_add_u64 v[102:103], v[102:103], 0, s[22:23]
	s_add_i32 m0, s82, 0x21000
	s_nop 0
	global_load_lds_dwordx4 v[102:103], off
.Lbr3_skipB:
	s_waitcnt vmcnt(8)
	s_waitcnt lgkmcnt(0)
	s_barrier
	s_setprio 1
	s_waitcnt lgkmcnt(0)
	v_mfma_f32_16x16x32_bf16 v[128:131], v[132:135], v[164:167], v[128:131]
	v_mfma_f32_16x16x32_bf16 v[124:127], v[140:143], v[164:167], v[124:127]
	v_mfma_f32_16x16x32_bf16 v[120:123], v[132:135], v[172:175], v[120:123]
	v_mfma_f32_16x16x32_bf16 v[116:119], v[140:143], v[172:175], v[116:119]
	v_mfma_f32_16x16x32_bf16 v[112:115], v[132:135], v[180:183], v[112:115]
	v_mfma_f32_16x16x32_bf16 v[108:111], v[140:143], v[180:183], v[108:111]
	v_mfma_f32_16x16x32_bf16 v[102:105], v[132:135], v[200:203], v[104:107]
	v_mfma_f32_16x16x32_bf16 v[98:101], v[140:143], v[200:203], v[98:101]
	v_mfma_f32_16x16x32_bf16 v[128:131], v[136:139], v[168:171], v[128:131]
	v_mfma_f32_16x16x32_bf16 v[124:127], v[144:147], v[168:171], v[124:127]
	v_mfma_f32_16x16x32_bf16 v[120:123], v[136:139], v[176:179], v[120:123]
	v_mfma_f32_16x16x32_bf16 v[116:119], v[144:147], v[176:179], v[116:119]
	v_mfma_f32_16x16x32_bf16 v[112:115], v[136:139], v[184:187], v[112:115]
	v_mfma_f32_16x16x32_bf16 v[108:111], v[144:147], v[184:187], v[108:111]
	v_mfma_f32_16x16x32_bf16 v[104:107], v[136:139], v[204:207], v[102:105]
	v_mfma_f32_16x16x32_bf16 v[100:103], v[144:147], v[204:207], v[98:101]
	s_setprio 0
	s_setprio 1
	v_mfma_f32_16x16x32_bf16 v[92:95], v[148:151], v[164:167], v[92:95]
	v_mfma_f32_16x16x32_bf16 v[88:91], v[156:159], v[164:167], v[88:91]
	v_mfma_f32_16x16x32_bf16 v[84:87], v[148:151], v[172:175], v[84:87]
	v_mfma_f32_16x16x32_bf16 v[80:83], v[156:159], v[172:175], v[80:83]
	v_mfma_f32_16x16x32_bf16 v[76:79], v[148:151], v[180:183], v[76:79]
	v_mfma_f32_16x16x32_bf16 v[72:75], v[156:159], v[180:183], v[72:75]
	v_mfma_f32_16x16x32_bf16 v[68:71], v[148:151], v[200:203], v[68:71]
	v_mfma_f32_16x16x32_bf16 v[64:67], v[156:159], v[200:203], v[64:67]
	v_mfma_f32_16x16x32_bf16 v[92:95], v[152:155], v[168:171], v[92:95]
	v_mfma_f32_16x16x32_bf16 v[88:91], v[160:163], v[168:171], v[88:91]
	v_mfma_f32_16x16x32_bf16 v[84:87], v[152:155], v[176:179], v[84:87]
	v_mfma_f32_16x16x32_bf16 v[80:83], v[160:163], v[176:179], v[80:83]
	v_mfma_f32_16x16x32_bf16 v[76:79], v[152:155], v[184:187], v[76:79]
	v_mfma_f32_16x16x32_bf16 v[72:75], v[160:163], v[184:187], v[72:75]
	v_mfma_f32_16x16x32_bf16 v[68:71], v[152:155], v[204:207], v[68:71]
	v_mfma_f32_16x16x32_bf16 v[64:67], v[160:163], v[204:207], v[64:67]
	s_setprio 0
	s_barrier
	s_add_i32 s22, s67, s82
	v_lshl_add_u64 v[98:99], v[208:209], 0, s[56:57]
	s_mov_b32 m0, s22
	ds_read_b128 v[164:167], v239 offset:49152
	ds_read_b128 v[168:171], v239 offset:50176
	ds_read_b128 v[172:175], v239 offset:51200
	ds_read_b128 v[176:179], v239 offset:52224
	ds_read_b128 v[180:183], v239 offset:53248
	ds_read_b128 v[184:187], v239 offset:54272
	ds_read_b128 v[200:203], v239 offset:55296
	ds_read_b128 v[204:207], v239 offset:56320
	global_load_lds_dwordx4 v[98:99], off
	v_lshl_add_u64 v[98:99], v[210:211], 0, s[56:57]
	s_add_i32 m0, s22, 0x2000
	s_add_i32 s22, s79, s82
	global_load_lds_dwordx4 v[98:99], off
	v_lshl_add_u64 v[98:99], v[212:213], 0, s[56:57]
	s_mov_b32 m0, s22
	s_nop 0
	global_load_lds_dwordx4 v[98:99], off
	v_lshl_add_u64 v[98:99], v[214:215], 0, s[56:57]
	s_add_i32 m0, s22, 0x2000
	s_nop 0
	global_load_lds_dwordx4 v[98:99], off
	v_lshl_add_u64 v[98:99], v[216:217], 0, s[56:57]
	s_mov_b32 m0, s91
	s_nop 0
	global_load_lds_dwordx4 v[98:99], off
	v_lshl_add_u64 v[98:99], v[218:219], 0, s[56:57]
	s_mov_b32 m0, s92
	s_nop 0
	global_load_lds_dwordx4 v[98:99], off
	s_waitcnt vmcnt(8)
	s_waitcnt lgkmcnt(0)
	s_barrier
	s_setprio 1
	s_waitcnt lgkmcnt(0)
	v_mfma_f32_16x16x32_bf16 v[60:63], v[132:135], v[164:167], v[60:63]
	v_mfma_f32_16x16x32_bf16 v[56:59], v[140:143], v[164:167], v[56:59]
	v_mfma_f32_16x16x32_bf16 v[52:55], v[132:135], v[172:175], v[52:55]
	v_mfma_f32_16x16x32_bf16 v[48:51], v[140:143], v[172:175], v[48:51]
	v_mfma_f32_16x16x32_bf16 v[44:47], v[132:135], v[180:183], v[44:47]
	v_mfma_f32_16x16x32_bf16 v[40:43], v[140:143], v[180:183], v[40:43]
	v_mfma_f32_16x16x32_bf16 v[36:39], v[132:135], v[200:203], v[36:39]
	v_mfma_f32_16x16x32_bf16 v[32:35], v[140:143], v[200:203], v[32:35]
	v_mfma_f32_16x16x32_bf16 v[60:63], v[136:139], v[168:171], v[60:63]
	v_mfma_f32_16x16x32_bf16 v[56:59], v[144:147], v[168:171], v[56:59]
	v_mfma_f32_16x16x32_bf16 v[52:55], v[136:139], v[176:179], v[52:55]
	v_mfma_f32_16x16x32_bf16 v[48:51], v[144:147], v[176:179], v[48:51]
	v_mfma_f32_16x16x32_bf16 v[44:47], v[136:139], v[184:187], v[44:47]
	v_mfma_f32_16x16x32_bf16 v[40:43], v[144:147], v[184:187], v[40:43]
	v_mfma_f32_16x16x32_bf16 v[36:39], v[136:139], v[204:207], v[36:39]
	v_mfma_f32_16x16x32_bf16 v[32:35], v[144:147], v[204:207], v[32:35]
	s_setprio 0
	s_setprio 1
	v_mfma_f32_16x16x32_bf16 v[28:31], v[148:151], v[164:167], v[28:31]
	v_mfma_f32_16x16x32_bf16 v[24:27], v[156:159], v[164:167], v[24:27]
	v_mfma_f32_16x16x32_bf16 v[20:23], v[148:151], v[172:175], v[20:23]
	v_mfma_f32_16x16x32_bf16 v[16:19], v[156:159], v[172:175], v[16:19]
	v_mfma_f32_16x16x32_bf16 v[12:15], v[148:151], v[180:183], v[12:15]
	v_mfma_f32_16x16x32_bf16 v[8:11], v[156:159], v[180:183], v[8:11]
	v_mfma_f32_16x16x32_bf16 v[4:7], v[148:151], v[200:203], v[4:7]
	v_mfma_f32_16x16x32_bf16 v[0:3], v[156:159], v[200:203], v[0:3]
	v_mfma_f32_16x16x32_bf16 v[28:31], v[152:155], v[168:171], v[28:31]
	v_mfma_f32_16x16x32_bf16 v[24:27], v[160:163], v[168:171], v[24:27]
	v_mfma_f32_16x16x32_bf16 v[20:23], v[152:155], v[176:179], v[20:23]
	v_mfma_f32_16x16x32_bf16 v[16:19], v[160:163], v[176:179], v[16:19]
	v_mfma_f32_16x16x32_bf16 v[12:15], v[152:155], v[184:187], v[12:15]
	v_mfma_f32_16x16x32_bf16 v[8:11], v[160:163], v[184:187], v[8:11]
	v_mfma_f32_16x16x32_bf16 v[4:7], v[152:155], v[204:207], v[4:7]
	v_mfma_f32_16x16x32_bf16 v[0:3], v[160:163], v[204:207], v[0:3]
	s_setprio 0
	s_barrier
	s_add_u32 s69, s69, 0x100
	s_addc_u32 vcc_lo, vcc_lo, 0
	s_add_u32 s8, s8, 0x100
	s_addc_u32 s9, s9, 0
	s_cmp_ge_i32 s78, s89
	s_mov_b32 s74, s78
	s_cbranch_scc0 .LBB0_1673

.LBB0_1676:
	s_lshl_b32 s8, s77, 8
	v_mov_b32_e32 v96, v237
	v_mov_b32_e32 v98, v236
	s_add_i32 s8, s8, s90
	s_ashr_i32 s77, s76, 31
	v_add_u32_e32 v200, s8, v96
	s_lshl_b32 s8, s35, 8
	s_or_b32 s8, s8, s93
	v_lshl_add_u32 v98, v98, 3, s8
	s_lshl_b64 s[8:9], s[76:77], 25
	s_add_u32 s74, s87, s8
	s_addc_u32 s75, s88, s9
	s_cmp_gt_i32 s76, 1
	s_cselect_b64 s[78:79], -1, 0
	s_cmp_lt_i32 s76, 2
	s_cselect_b64 s[22:23], -1, 0
	s_cmp_lg_u64 s[22:23], 0
	s_addc_u32 s8, s76, 0
	s_ashr_i32 s9, s8, 31
	v_ashrrev_i32_e32 v201, 31, v200
	s_lshl_b64 s[8:9], s[8:9], 25
	v_ashrrev_i32_e32 v99, 31, v98
	v_lshlrev_b64 v[132:133], 10, v[200:201]
	s_add_u32 s76, s87, s8
	v_lshl_add_u64 v[132:133], v[132:133], 0, v[98:99]
	v_add_u32_e32 v206, 16, v200
	s_addc_u32 s77, s88, s9
	v_lshlrev_b64 v[132:133], 1, v[132:133]
	v_ashrrev_i32_e32 v207, 31, v206
	v_lshl_add_u64 v[134:135], s[74:75], 0, v[132:133]
	v_lshl_add_u64 v[216:217], s[76:77], 0, v[132:133]
	v_lshlrev_b64 v[132:133], 10, v[206:207]
	v_lshl_add_u64 v[132:133], v[132:133], 0, v[98:99]
	v_add_u32_e32 v204, 32, v200
	v_lshlrev_b64 v[132:133], 1, v[132:133]
	v_ashrrev_i32_e32 v205, 31, v204
	s_cmp_lg_u64 s[78:79], 0
	s_cbranch_scc1 .Lbr3_a0_seg2
	global_load_dwordx4 v[208:211], v[134:135], off
	global_load_dwordx4 v[180:183], v[216:217], off offset:256
	v_lshl_add_u64 v[136:137], s[74:75], 0, v[132:133]
	global_load_dwordx4 v[184:187], v[134:135], off offset:256
	global_load_dwordx4 v[176:179], v[136:137], off
	v_lshlrev_b64 v[134:135], 10, v[204:205]
	v_lshl_add_u64 v[134:135], v[134:135], 0, v[98:99]
	v_add_u32_e32 v202, 48, v200
	v_lshl_add_u64 v[132:133], s[76:77], 0, v[132:133]
	v_lshlrev_b64 v[134:135], 1, v[134:135]
	v_ashrrev_i32_e32 v203, 31, v202
	global_load_dwordx4 v[172:175], v[132:133], off
	global_load_dwordx4 v[168:171], v[136:137], off offset:256
	v_lshl_add_u64 v[136:137], s[74:75], 0, v[134:135]
	global_load_dwordx4 v[164:167], v[132:133], off offset:256
	global_load_dwordx4 v[160:163], v[136:137], off
	v_lshl_add_u64 v[132:133], s[76:77], 0, v[134:135]
	v_lshlrev_b64 v[134:135], 10, v[202:203]
	v_lshl_add_u64 v[134:135], v[134:135], 0, v[98:99]
	v_lshlrev_b64 v[134:135], 1, v[134:135]
	global_load_dwordx4 v[156:159], v[132:133], off
	global_load_dwordx4 v[152:155], v[136:137], off offset:256
	v_lshl_add_u64 v[136:137], s[74:75], 0, v[134:135]
	global_load_dwordx4 v[148:151], v[132:133], off offset:256
	global_load_dwordx4 v[144:147], v[136:137], off
	v_lshl_add_u64 v[132:133], s[76:77], 0, v[134:135]
	global_load_dwordx4 v[140:143], v[132:133], off
	s_nop 0
	global_load_dwordx4 v[136:139], v[136:137], off offset:256
	s_nop 0
	global_load_dwordx4 v[132:135], v[132:133], off offset:256
	s_nop 0
	global_load_dwordx4 v[244:247], v[216:217], off
	v_lshlrev_b64 v[240:241], 11, v[200:201]
	s_mov_b64 s[8:9], -1
	s_and_b64 vcc, exec, s[22:23]
	s_waitcnt vmcnt(0)
	s_branch .Lbr3_a0_join
.Lbr3_a0_seg2:
	v_lshl_add_u64 v[136:137], s[74:75], 0, v[132:133]
	v_lshlrev_b64 v[134:135], 10, v[204:205]
	v_lshl_add_u64 v[134:135], v[134:135], 0, v[98:99]
	v_add_u32_e32 v202, 48, v200
	v_lshl_add_u64 v[132:133], s[76:77], 0, v[132:133]
	v_lshlrev_b64 v[134:135], 1, v[134:135]
	v_ashrrev_i32_e32 v203, 31, v202
	v_lshl_add_u64 v[136:137], s[74:75], 0, v[134:135]
	v_lshl_add_u64 v[132:133], s[76:77], 0, v[134:135]
	v_lshlrev_b64 v[134:135], 10, v[202:203]
	v_lshl_add_u64 v[134:135], v[134:135], 0, v[98:99]
	v_lshlrev_b64 v[134:135], 1, v[134:135]
	v_lshl_add_u64 v[136:137], s[74:75], 0, v[134:135]
	v_lshl_add_u64 v[132:133], s[76:77], 0, v[134:135]
	v_lshlrev_b64 v[240:241], 11, v[200:201]
	s_mov_b64 s[8:9], -1
	s_and_b64 vcc, exec, s[22:23]
	s_mov_b64 s[56:57], 0x80
	s_waitcnt vmcnt(0)
	v_lshlrev_b32_e32 v244, 4, v220
	v_add_u32_e32 v245, 0x10000, v244
	v_add_u32_e32 v246, 0x21000, v244
	ds_read_b128 v[208:211], v245
	ds_read_b128 v[184:187], v245 offset:8192
	ds_read_b128 v[176:179], v245 offset:16384
	ds_read_b128 v[168:171], v245 offset:24576
	ds_read_b128 v[160:163], v244
	ds_read_b128 v[152:155], v244 offset:8192
	ds_read_b128 v[144:147], v244 offset:16384
	ds_read_b128 v[136:139], v244 offset:24576
	s_waitcnt lgkmcnt(0)
.Lbr3_a0_join:
	v_lshlrev_b32_e32 v218, 16, v208
	v_and_b32_e32 v219, 0xffff0000, v208
	v_lshlrev_b32_e32 v214, 16, v209
	v_and_b32_e32 v215, 0xffff0000, v209
	v_lshl_add_u64 v[208:209], s[52:53], 0, v[240:241]
	v_lshlrev_b32_e32 v212, 16, v210
	v_and_b32_e32 v213, 0xffff0000, v210
	v_lshlrev_b32_e32 v210, 16, v211
	v_and_b32_e32 v211, 0xffff0000, v211
	v_lshl_add_u64 v[208:209], v[98:99], 1, v[208:209]
	s_cbranch_vccnz .LBB0_1678
	v_pk_mul_f32 v[240:241], v[128:129], v[218:219]
	v_pk_mul_f32 v[242:243], v[130:131], v[214:215]
	v_pk_mul_f32 v[244:245], v[124:125], v[212:213]
	v_pk_mul_f32 v[246:247], v[126:127], v[210:211]
	v_cvt_pk_bf16_f32 v240, v240, v241
	v_cvt_pk_bf16_f32 v241, v242, v243
	v_cvt_pk_bf16_f32 v242, v244, v245
	v_cvt_pk_bf16_f32 v243, v246, v247
	s_mov_b64 s[8:9], 0
	global_store_dwordx4 v[208:209], v[240:243], off

.LBB0_1708:
	v_add_u32_e32 v210, 0x80, v200
	v_ashrrev_i32_e32 v211, 31, v210
	v_lshlrev_b64 v[132:133], 10, v[210:211]
	v_lshl_add_u64 v[132:133], v[132:133], 0, v[98:99]
	v_add_u32_e32 v204, 0x90, v200
	v_lshlrev_b64 v[132:133], 1, v[132:133]
	v_ashrrev_i32_e32 v205, 31, v204
	v_lshl_add_u64 v[134:135], s[74:75], 0, v[132:133]
	v_lshl_add_u64 v[212:213], s[76:77], 0, v[132:133]
	v_lshlrev_b64 v[132:133], 10, v[204:205]
	v_lshl_add_u64 v[132:133], v[132:133], 0, v[98:99]
	v_add_u32_e32 v202, 0xa0, v200
	v_lshlrev_b64 v[132:133], 1, v[132:133]
	v_ashrrev_i32_e32 v203, 31, v202
	s_cmp_eq_u64 s[8:9], 0
	s_cbranch_scc1 .Lbr3_a1_seg2
	global_load_dwordx4 v[206:209], v[134:135], off
	global_load_dwordx4 v[180:183], v[212:213], off offset:256
	v_lshl_add_u64 v[136:137], s[74:75], 0, v[132:133]
	global_load_dwordx4 v[184:187], v[134:135], off offset:256
	global_load_dwordx4 v[176:179], v[136:137], off
	v_lshlrev_b64 v[134:135], 10, v[202:203]
	v_lshl_add_u64 v[134:135], v[134:135], 0, v[98:99]
	v_add_u32_e32 v200, 0xb0, v200
	v_lshl_add_u64 v[132:133], s[76:77], 0, v[132:133]
	v_lshlrev_b64 v[134:135], 1, v[134:135]
	v_ashrrev_i32_e32 v201, 31, v200
	global_load_dwordx4 v[172:175], v[132:133], off
	global_load_dwordx4 v[168:171], v[136:137], off offset:256
	v_lshl_add_u64 v[136:137], s[74:75], 0, v[134:135]
	global_load_dwordx4 v[164:167], v[132:133], off offset:256
	global_load_dwordx4 v[160:163], v[136:137], off
	v_lshl_add_u64 v[132:133], s[76:77], 0, v[134:135]
	v_lshlrev_b64 v[134:135], 10, v[200:201]
	v_lshl_add_u64 v[134:135], v[134:135], 0, v[98:99]
	v_lshlrev_b64 v[134:135], 1, v[134:135]
	global_load_dwordx4 v[156:159], v[132:133], off
	global_load_dwordx4 v[152:155], v[136:137], off offset:256
	v_lshl_add_u64 v[136:137], s[74:75], 0, v[134:135]
	global_load_dwordx4 v[148:151], v[132:133], off offset:256
	global_load_dwordx4 v[144:147], v[136:137], off
	v_lshl_add_u64 v[132:133], s[76:77], 0, v[134:135]
	global_load_dwordx4 v[140:143], v[132:133], off
	s_nop 0
	global_load_dwordx4 v[136:139], v[136:137], off offset:256
	s_nop 0
	global_load_dwordx4 v[132:135], v[132:133], off offset:256
	s_nop 0
	global_load_dwordx4 v[244:247], v[212:213], off
	v_lshlrev_b64 v[210:211], 11, v[210:211]
	v_lshl_add_u64 v[218:219], s[52:53], 0, v[210:211]
	s_mov_b64 s[74:75], -1
	s_and_b64 vcc, exec, s[8:9]
	s_waitcnt vmcnt(0)
	s_branch .Lbr3_a1_join
.Lbr3_a1_seg2:
	v_lshl_add_u64 v[136:137], s[74:75], 0, v[132:133]
	v_lshlrev_b64 v[134:135], 10, v[202:203]
	v_lshl_add_u64 v[134:135], v[134:135], 0, v[98:99]
	v_add_u32_e32 v200, 0xb0, v200
	v_lshl_add_u64 v[132:133], s[76:77], 0, v[132:133]
	v_lshlrev_b64 v[134:135], 1, v[134:135]
	v_ashrrev_i32_e32 v201, 31, v200
	v_lshl_add_u64 v[136:137], s[74:75], 0, v[134:135]
	v_lshl_add_u64 v[132:133], s[76:77], 0, v[134:135]
	v_lshlrev_b64 v[134:135], 10, v[200:201]
	v_lshl_add_u64 v[134:135], v[134:135], 0, v[98:99]
	v_lshlrev_b64 v[134:135], 1, v[134:135]
	v_lshl_add_u64 v[136:137], s[74:75], 0, v[134:135]
	v_lshl_add_u64 v[132:133], s[76:77], 0, v[134:135]
	v_lshlrev_b64 v[210:211], 11, v[210:211]
	v_lshl_add_u64 v[218:219], s[52:53], 0, v[210:211]
	s_mov_b64 s[74:75], -1
	s_and_b64 vcc, exec, s[8:9]
	s_waitcnt vmcnt(0)
	v_lshlrev_b32_e32 v244, 4, v220
	v_add_u32_e32 v245, 0x10000, v244
	v_add_u32_e32 v246, 0x21000, v244
	ds_read_b128 v[206:209], v245 offset:32768
	ds_read_b128 v[184:187], v245 offset:40960
	ds_read_b128 v[176:179], v245 offset:49152
	ds_read_b128 v[168:171], v245 offset:57344
	ds_read_b128 v[160:163], v244 offset:32768
	ds_read_b128 v[152:155], v244 offset:40960
	ds_read_b128 v[144:147], v246
	ds_read_b128 v[136:139], v246 offset:8192
	s_waitcnt lgkmcnt(0)
.Lbr3_a1_join:
	v_lshlrev_b32_e32 v216, 16, v206
	v_and_b32_e32 v217, 0xffff0000, v206
	v_lshlrev_b32_e32 v214, 16, v207
	v_and_b32_e32 v215, 0xffff0000, v207
	v_lshlrev_b32_e32 v210, 16, v208
	v_and_b32_e32 v211, 0xffff0000, v208
	v_lshlrev_b32_e32 v208, 16, v209
	v_and_b32_e32 v209, 0xffff0000, v209
	v_lshl_add_u64 v[206:207], v[98:99], 1, v[218:219]
	s_cbranch_vccnz .LBB0_1710
	v_pk_mul_f32 v[218:219], v[60:61], v[216:217]
	v_pk_mul_f32 v[242:243], v[62:63], v[214:215]
	v_pk_mul_f32 v[244:245], v[56:57], v[210:211]
	v_pk_mul_f32 v[246:247], v[58:59], v[208:209]
	v_cvt_pk_bf16_f32 v240, v218, v219
	v_cvt_pk_bf16_f32 v241, v242, v243
	v_cvt_pk_bf16_f32 v242, v244, v245
	v_cvt_pk_bf16_f32 v243, v246, v247
	s_mov_b64 s[74:75], 0
	global_store_dwordx4 v[206:207], v[240:243], off
